# fused epilogues: one 16-byte sc1 load for the four row partials instead of four serialized dword loads (stacked)
# baseline (speedup 1.0000x reference)
.LBB0_473:
	s_waitcnt vmcnt(0) lgkmcnt(0)
	s_barrier
	s_and_b64 vcc, exec, s[42:43]
	s_cbranch_vccnz .LBB0_475
	global_load_dwordx4 v[140:143], v[140:141], off sc1
	s_waitcnt vmcnt(0)
	v_add_f32_e32 v140, 0, v140
	v_add_f32_e32 v140, v140, v141
	v_add_f32_e32 v140, v140, v142
	v_add_f32_e32 v140, v140, v143
	v_fmamk_f32 v140, v140, 0x3a800000, v244
	v_cmp_gt_f32_e32 vcc, s7, v140
	v_mul_f32_e32 v141, 0x4b800000, v140
	s_nop 0
	v_cndmask_b32_e32 v140, v140, v141, vcc
	v_rsq_f32_e32 v140, v140
	s_nop 0
	v_mul_f32_e32 v141, 0x45800000, v140
	v_cndmask_b32_e32 v140, v140, v141, vcc
	v_lshl_add_u32 v141, v228, 2, 0
	v_add_u32_e32 v141, 0x21000, v141
	ds_write_b32 v141, v140

.LBB0_503:
	v_readlane_b32 s2, v253, 23
	s_waitcnt vmcnt(0) lgkmcnt(0)
	s_barrier
	s_nop 0
	v_mov_b32_e32 v2, s2
	ds_read_b32 v2, v2
	s_xor_b64 s[2:3], s[46:47], -1
	s_waitcnt lgkmcnt(0)
	v_cmp_eq_u32_e32 vcc, 0, v2
	s_or_b64 s[2:3], s[2:3], vcc
	s_and_b64 vcc, exec, s[2:3]
	s_cbranch_vccnz .LBB0_505
	global_load_dwordx4 v[0:3], v[0:1], off sc1
	v_readlane_b32 s2, v253, 29
	v_readlane_b32 s3, v253, 30
	s_add_u32 s2, s2, s34
	s_addc_u32 s3, s3, s35
	s_waitcnt vmcnt(0)
	v_add_f32_e32 v0, 0, v0
	v_add_f32_e32 v0, v0, v1
	v_add_f32_e32 v0, v0, v2
	v_add_f32_e32 v0, v0, v3
	v_fmamk_f32 v0, v0, 0x3a800000, v244
	v_cmp_gt_f32_e32 vcc, s7, v0
	v_mul_f32_e32 v1, 0x4b800000, v0
	s_nop 0
	v_cndmask_b32_e32 v0, v0, v1, vcc
	v_rsq_f32_e32 v0, v0
	s_nop 0
	v_mul_f32_e32 v1, 0x45800000, v0
	v_cndmask_b32_e32 v2, v0, v1, vcc
	v_lshl_add_u64 v[0:1], v[228:229], 2, s[2:3]
	global_store_dword v[0:1], v2, off

.LBB0_693:
	s_waitcnt vmcnt(0) lgkmcnt(0)
	s_barrier
	s_and_b64 vcc, exec, s[42:43]
	s_cbranch_vccnz .LBB0_695
	global_load_dwordx4 v[124:127], v[124:125], off sc1
	s_waitcnt vmcnt(0)
	v_add_f32_e32 v124, 0, v124
	v_add_f32_e32 v124, v124, v125
	v_add_f32_e32 v124, v124, v126
	v_add_f32_e32 v124, v124, v127
	v_fmamk_f32 v124, v124, 0x3a800000, v244
	v_cmp_gt_f32_e32 vcc, s7, v124
	v_mul_f32_e32 v125, 0x4b800000, v124
	s_nop 0
	v_cndmask_b32_e32 v124, v124, v125, vcc
	v_rsq_f32_e32 v124, v124
	s_nop 0
	v_mul_f32_e32 v125, 0x45800000, v124
	v_cndmask_b32_e32 v124, v124, v125, vcc
	v_lshl_add_u32 v125, v228, 2, 0
	v_add_u32_e32 v125, 0x21000, v125
	ds_write_b32 v125, v124

.LBB0_788:
	v_readlane_b32 s2, v253, 23
	s_waitcnt vmcnt(0) lgkmcnt(0)
	s_barrier
	s_nop 0
	v_mov_b32_e32 v2, s2
	ds_read_b32 v2, v2
	s_xor_b64 s[2:3], s[70:71], -1
	s_waitcnt lgkmcnt(0)
	v_cmp_eq_u32_e32 vcc, 0, v2
	s_or_b64 s[2:3], s[2:3], vcc
	s_and_b64 vcc, exec, s[2:3]
	s_cbranch_vccnz .LBB0_790
	global_load_dwordx4 v[0:3], v[0:1], off sc1
	v_readlane_b32 s2, v253, 29
	v_readlane_b32 s3, v253, 30
	s_add_u32 s2, s2, s34
	s_addc_u32 s3, s3, s35
	s_waitcnt vmcnt(0)
	v_add_f32_e32 v0, 0, v0
	v_add_f32_e32 v0, v0, v1
	v_add_f32_e32 v0, v0, v2
	v_add_f32_e32 v0, v0, v3
	v_fmamk_f32 v0, v0, 0x3a800000, v244
	v_cmp_gt_f32_e32 vcc, s7, v0
	v_mul_f32_e32 v1, 0x4b800000, v0
	s_nop 0
	v_cndmask_b32_e32 v0, v0, v1, vcc
	v_rsq_f32_e32 v0, v0
	s_nop 0
	v_mul_f32_e32 v1, 0x45800000, v0
	v_cndmask_b32_e32 v2, v0, v1, vcc
	v_lshl_add_u64 v[0:1], v[228:229], 2, s[2:3]
	global_store_dword v[0:1], v2, off
